# v046 + per-unit s_waitcnt vmcnt(0) ahead of the K-loop removed in in-proj / gate-up phases (the loop's counted waits already cover the prefetched tiles; vmcnt retires in issue order)
# speedup vs baseline: 1.0053x; 1.0013x over previous
; #define PG8_STAGE(bufoff, gbase, voff) do { _Pragma("unroll") for (int _i = 0; _i < 2; ++_i) \
;         __builtin_amdgcn_global_load_lds((const unsigned*)((const char*)(gbase) + (voff)[_i]), (PG8_LAS unsigned*)(lds + (bufoff) + ldsw + _i * 8192), 16, 0, 0); } while (0)
; #define PG8_LDA(dst, b, h) do { _Pragma("unroll") for (int m = 0; m < 4; ++m) _Pragma("unroll") for (int k = 0; k < 2; ++k) dst[m][k] = *(const PG8_LAS bf16x8*)(lds + PG8_SA(b, h) + aoff + m * 2048 + k * 1024); } while (0)
; #define PG8_LDB(dst, b, h) do { _Pragma("unroll") for (int n = 0; n < 2; ++n) _Pragma("unroll") for (int k = 0; k < 2; ++k) dst[n][k] = *(const PG8_LAS bf16x8*)(lds + PG8_SB(b, h) + boff + n * 2048 + k * 1024); } while (0)
; #define PG8_MMA(ai, bj, At, Bt) do { __builtin_amdgcn_s_setprio(1); _Pragma("unroll") for (int m = 0; m < 4; ++m) _Pragma("unroll") for (int n = 0; n < 2; ++n) _Pragma("unroll") for (int k = 0; k < 2; ++k) \
;         acc[ai][bj][m][n] = __builtin_amdgcn_mfma_f32_16x16x32_bf16(Bt[n][k], At[m][k], acc[ai][bj][m][n], 0, 0, 0); __builtin_amdgcn_s_setprio(0); } while (0)
; #define PG8_WAIT_V(n) asm volatile("s_waitcnt vmcnt(" #n ")" ::: "memory")
; #define PG8_WAIT_L(n) asm volatile("s_waitcnt lgkmcnt(" #n ")" ::: "memory")
; template <class Epi, class Sched, bool ALIGN_EPI = false, bool SP2 = false, bool PAIR_ACC = false>
; __device__ __forceinline__ void gemm_phase(PG8_LAS unsigned char* lds, const Gemm g, const Sched& S, const Epi& E) {
;     ...
;         const char* nA = has_next ? (const char*)g.A + (size_t)nxt.pm * tstep + (size_t)(nxt.pn / g.a_div) * g.a_sel : cA; const char* nB = has_next ? (const char*)g.Bt + (size_t)nxt.pn * tstep : cB;
;         for (int t = 0; t < nt; t += 2) {
;             const bool last = (t == nt - 2);
;             const char* a1 = cA + (size_t)(t + 1) * kstep;
;             const char* a2 = last ? nA : cA + (size_t)(t + 2) * kstep; const char* b2 = last ? nB : cB + (size_t)(t + 2) * kstep;
;             const char* a3 = a2 + kstep; const char* b3 = b2 + kstep;
;             if (last && has_next) S.a_ready(nxt);
;             if constexpr (SP2) {
;             PG8_LDB(B0, 0, 0); PG8_LDB(B1, 0, 1); PG8_SCHED; PG8_LDA(At, 0, 0); PG8_STAGE(PG8_SA(1, 1), a1 + hstep, voffA);
;             PG8_WAIT_V(8); PG8_WAIT_L(0); PG8_BAR; PG8_MMA(0, 0, At, B0); PG8_MMA(0, 1, At, B1); PG8_BAR; PG8_SCHED;
.LBB0_189:
	s_mov_b32 s80, s21
	s_ashr_i32 s81, s21, 31
	s_lshl_b64 s[18:19], s[80:81], 19
	s_add_u32 s84, s23, s18
	s_addc_u32 s85, s61, s19
	s_mov_b32 s78, s17
	s_and_b64 s[18:19], s[82:83], exec
	s_cselect_b32 s13, s85, s11
	s_cselect_b32 s17, s84, s10
	s_ashr_i32 s79, s78, 31
	s_lshl_b64 s[18:19], s[78:79], 19
	s_add_u32 s86, s63, s18
	s_addc_u32 s87, s65, s19
	s_and_b64 s[18:19], s[82:83], exec
	s_cselect_b32 s20, s87, s15
	s_cselect_b32 s21, s86, s14
	s_add_u32 s10, s10, 0x40080
	s_addc_u32 s11, s11, 0
	s_add_u32 s30, s14, 0x100
	s_addc_u32 s38, s15, 0
	s_mov_b32 s39, -2
	s_waitcnt lgkmcnt(0)
	ds_read_b128 v[130:133], v196
	ds_read_b128 v[134:137], v196 offset:1024
	ds_read_b128 v[138:141], v196 offset:2048
	ds_read_b128 v[142:145], v196 offset:3072
	ds_read_b128 v[178:181], v197
	ds_read_b128 v[182:185], v197 offset:1024
	ds_read_b128 v[186:189], v197 offset:2048
	ds_read_b128 v[190:193], v197 offset:3072
	s_add_u32 s14, s10, 0xfffc0080
	s_addc_u32 s15, s11, -1
	s_cmp_eq_u32 s39, 12
	s_cselect_b32 s19, s13, s15
	s_cselect_b32 s18, s17, s14
	s_cselect_b32 s15, s20, s38
	s_cselect_b32 s14, s21, s30
	v_lshl_add_u64 v[194:195], s[10:11], 0, v[170:171]
	s_add_i32 m0, s69, 0xc000
	ds_read_b128 v[206:209], v198
	ds_read_b128 v[210:213], v198 offset:1024
	ds_read_b128 v[214:217], v198 offset:2048
	ds_read_b128 v[218:221], v198 offset:3072
	ds_read_b128 v[222:225], v198 offset:4096
	ds_read_b128 v[226:229], v198 offset:5120
	ds_read_b128 v[230:233], v198 offset:6144
	ds_read_b128 v[234:237], v198 offset:7168
	global_load_lds_dwordx4 v[194:195], off
	v_lshl_add_u64 v[194:195], s[10:11], 0, v[174:175]
	s_add_i32 m0, s69, 0xe000
	s_nop 0
	global_load_lds_dwordx4 v[194:195], off
	s_waitcnt vmcnt(8)
	s_waitcnt lgkmcnt(0)
	s_barrier
	s_setprio 1
	s_waitcnt lgkmcnt(0)
	v_mfma_f32_16x16x32_bf16 v[126:129], v[130:133], v[206:209], 0
	v_mfma_f32_16x16x32_bf16 v[122:125], v[138:141], v[206:209], 0
	v_mfma_f32_16x16x32_bf16 v[110:113], v[130:133], v[214:217], 0
	v_mfma_f32_16x16x32_bf16 v[106:109], v[138:141], v[214:217], 0
	v_mfma_f32_16x16x32_bf16 v[94:97], v[130:133], v[222:225], 0
	v_mfma_f32_16x16x32_bf16 v[90:93], v[138:141], v[222:225], 0
	v_mfma_f32_16x16x32_bf16 v[78:81], v[130:133], v[230:233], 0
	v_mfma_f32_16x16x32_bf16 v[74:77], v[138:141], v[230:233], 0
	v_mfma_f32_16x16x32_bf16 v[126:129], v[134:137], v[210:213], v[126:129]
	v_mfma_f32_16x16x32_bf16 v[122:125], v[142:145], v[210:213], v[122:125]
	v_mfma_f32_16x16x32_bf16 v[110:113], v[134:137], v[218:221], v[110:113]
	v_mfma_f32_16x16x32_bf16 v[106:109], v[142:145], v[218:221], v[106:109]
	v_mfma_f32_16x16x32_bf16 v[94:97], v[134:137], v[226:229], v[94:97]
	v_mfma_f32_16x16x32_bf16 v[90:93], v[142:145], v[226:229], v[90:93]
	v_mfma_f32_16x16x32_bf16 v[78:81], v[134:137], v[234:237], v[78:81]
	v_mfma_f32_16x16x32_bf16 v[74:77], v[142:145], v[234:237], v[74:77]
	s_setprio 0
	s_setprio 1
	v_mfma_f32_16x16x32_bf16 v[118:121], v[178:181], v[206:209], 0
	v_mfma_f32_16x16x32_bf16 v[114:117], v[186:189], v[206:209], 0
	v_mfma_f32_16x16x32_bf16 v[102:105], v[178:181], v[214:217], 0
	v_mfma_f32_16x16x32_bf16 v[98:101], v[186:189], v[214:217], 0
	v_mfma_f32_16x16x32_bf16 v[86:89], v[178:181], v[222:225], 0
	v_mfma_f32_16x16x32_bf16 v[82:85], v[186:189], v[222:225], 0
	v_mfma_f32_16x16x32_bf16 v[70:73], v[178:181], v[230:233], 0
	v_mfma_f32_16x16x32_bf16 v[66:69], v[186:189], v[230:233], 0
	v_mfma_f32_16x16x32_bf16 v[118:121], v[182:185], v[210:213], v[118:121]
	v_mfma_f32_16x16x32_bf16 v[114:117], v[190:193], v[210:213], v[114:117]
	v_mfma_f32_16x16x32_bf16 v[102:105], v[182:185], v[218:221], v[102:105]
	v_mfma_f32_16x16x32_bf16 v[98:101], v[190:193], v[218:221], v[98:101]
	v_mfma_f32_16x16x32_bf16 v[86:89], v[182:185], v[226:229], v[86:89]
	v_mfma_f32_16x16x32_bf16 v[82:85], v[190:193], v[226:229], v[82:85]
	v_mfma_f32_16x16x32_bf16 v[70:73], v[182:185], v[234:237], v[70:73]
	v_mfma_f32_16x16x32_bf16 v[66:69], v[190:193], v[234:237], v[66:69]
	s_setprio 0
	s_barrier
; #define PG8_STAGE(bufoff, gbase, voff) do { _Pragma("unroll") for (int _i = 0; _i < 2; ++_i) \
;         __builtin_amdgcn_global_load_lds((const unsigned*)((const char*)(gbase) + (voff)[_i]), (PG8_LAS unsigned*)(lds + (bufoff) + ldsw + _i * 8192), 16, 0, 0); } while (0)
; #define PG8_LDA(dst, b, h) do { _Pragma("unroll") for (int m = 0; m < 4; ++m) _Pragma("unroll") for (int k = 0; k < 2; ++k) dst[m][k] = *(const PG8_LAS bf16x8*)(lds + PG8_SA(b, h) + aoff + m * 2048 + k * 1024); } while (0)
; #define PG8_MMA(ai, bj, At, Bt) do { __builtin_amdgcn_s_setprio(1); _Pragma("unroll") for (int m = 0; m < 4; ++m) _Pragma("unroll") for (int n = 0; n < 2; ++n) _Pragma("unroll") for (int k = 0; k < 2; ++k) \
;         acc[ai][bj][m][n] = __builtin_amdgcn_mfma_f32_16x16x32_bf16(Bt[n][k], At[m][k], acc[ai][bj][m][n], 0, 0, 0); __builtin_amdgcn_s_setprio(0); } while (0)
; #define PG8_WAIT_V(n) asm volatile("s_waitcnt vmcnt(" #n ")" ::: "memory")
; #define PG8_WAIT_L(n) asm volatile("s_waitcnt lgkmcnt(" #n ")" ::: "memory")
; #define PG8_BAR __builtin_amdgcn_s_barrier()
; #define PG8_SCHED __builtin_amdgcn_sched_barrier(0)
; template <class Epi, class Sched, bool ALIGN_EPI = false, bool SP2 = false, bool PAIR_ACC = false>
; __device__ __forceinline__ void gemm_phase(PG8_LAS unsigned char* lds, const Gemm g, const Sched& S, const Epi& E) {
;     ...
;             PG8_LDA(At, 0, 1); PG8_STAGE(PG8_SB(0, 0), b2, voffB); PG8_STAGE(PG8_SB(0, 1), b2 + hstep, voffB); PG8_STAGE(PG8_SA(0, 0), a2, voffA);
;             PG8_WAIT_V(8); PG8_WAIT_L(0); PG8_BAR; PG8_MMA(1, 0, At, B0); PG8_MMA(1, 1, At, B1); PG8_BAR; PG8_SCHED;
	s_add_i32 s40, s25, s67
	v_lshl_add_u64 v[194:195], s[14:15], 0, v[148:149]
	s_mov_b32 m0, s40
	ds_read_b128 v[206:209], v198 offset:16384
	ds_read_b128 v[210:213], v198 offset:17408
	ds_read_b128 v[214:217], v198 offset:18432
	ds_read_b128 v[218:221], v198 offset:19456
	ds_read_b128 v[222:225], v198 offset:20480
	ds_read_b128 v[226:229], v198 offset:21504
	ds_read_b128 v[230:233], v198 offset:22528
	ds_read_b128 v[234:237], v198 offset:23552
	global_load_lds_dwordx4 v[194:195], off
	s_add_i32 m0, s40, 0x2000
	s_add_u32 s40, s14, 0x40000
	v_lshl_add_u64 v[238:239], s[14:15], 0, v[152:153]
	s_addc_u32 s41, s15, 0
	s_add_i32 s79, s35, s67
	global_load_lds_dwordx4 v[238:239], off
	v_lshl_add_u64 v[240:241], s[40:41], 0, v[148:149]
	s_mov_b32 m0, s79
	v_lshl_add_u64 v[242:243], s[18:19], 0, v[150:151]
	global_load_lds_dwordx4 v[240:241], off
	v_lshl_add_u64 v[240:241], s[40:41], 0, v[152:153]
	s_add_i32 m0, s79, 0x2000
	s_nop 0
	global_load_lds_dwordx4 v[240:241], off
	v_lshl_add_u64 v[240:241], s[18:19], 0, v[146:147]
	s_mov_b32 m0, s69
	s_nop 0
	global_load_lds_dwordx4 v[240:241], off
	s_mov_b32 m0, s71
	s_nop 0
	global_load_lds_dwordx4 v[242:243], off
	s_waitcnt vmcnt(8)
	s_waitcnt lgkmcnt(0)
	s_barrier
	s_setprio 1
	s_waitcnt lgkmcnt(0)
	v_mfma_f32_16x16x32_bf16 v[62:65], v[130:133], v[206:209], 0
	v_mfma_f32_16x16x32_bf16 v[58:61], v[138:141], v[206:209], 0
	v_mfma_f32_16x16x32_bf16 v[46:49], v[130:133], v[214:217], 0
	v_mfma_f32_16x16x32_bf16 v[42:45], v[138:141], v[214:217], 0
	v_mfma_f32_16x16x32_bf16 v[30:33], v[130:133], v[222:225], 0
	v_mfma_f32_16x16x32_bf16 v[26:29], v[138:141], v[222:225], 0
	v_mfma_f32_16x16x32_bf16 v[14:17], v[130:133], v[230:233], 0
	v_mfma_f32_16x16x32_bf16 v[10:13], v[138:141], v[230:233], 0
	v_mfma_f32_16x16x32_bf16 v[62:65], v[134:137], v[210:213], v[62:65]
	v_mfma_f32_16x16x32_bf16 v[58:61], v[142:145], v[210:213], v[58:61]
	v_mfma_f32_16x16x32_bf16 v[46:49], v[134:137], v[218:221], v[46:49]
	v_mfma_f32_16x16x32_bf16 v[42:45], v[142:145], v[218:221], v[42:45]
	v_mfma_f32_16x16x32_bf16 v[30:33], v[134:137], v[226:229], v[30:33]
	v_mfma_f32_16x16x32_bf16 v[26:29], v[142:145], v[226:229], v[26:29]
	v_mfma_f32_16x16x32_bf16 v[14:17], v[134:137], v[234:237], v[14:17]
	v_mfma_f32_16x16x32_bf16 v[10:13], v[142:145], v[234:237], v[10:13]
	s_setprio 0
	s_setprio 1
	v_mfma_f32_16x16x32_bf16 v[54:57], v[178:181], v[206:209], 0
	v_mfma_f32_16x16x32_bf16 v[50:53], v[186:189], v[206:209], 0
	v_mfma_f32_16x16x32_bf16 v[38:41], v[178:181], v[214:217], 0
	v_mfma_f32_16x16x32_bf16 v[34:37], v[186:189], v[214:217], 0
	v_mfma_f32_16x16x32_bf16 v[22:25], v[178:181], v[222:225], 0
	v_mfma_f32_16x16x32_bf16 v[18:21], v[186:189], v[222:225], 0
	v_mfma_f32_16x16x32_bf16 v[6:9], v[178:181], v[230:233], 0
	v_mfma_f32_16x16x32_bf16 v[2:5], v[186:189], v[230:233], 0
	v_mfma_f32_16x16x32_bf16 v[54:57], v[182:185], v[210:213], v[54:57]
	v_mfma_f32_16x16x32_bf16 v[50:53], v[190:193], v[210:213], v[50:53]
	v_mfma_f32_16x16x32_bf16 v[38:41], v[182:185], v[218:221], v[38:41]
	v_mfma_f32_16x16x32_bf16 v[34:37], v[190:193], v[218:221], v[34:37]
	v_mfma_f32_16x16x32_bf16 v[22:25], v[182:185], v[226:229], v[22:25]
	v_mfma_f32_16x16x32_bf16 v[18:21], v[190:193], v[226:229], v[18:21]
	v_mfma_f32_16x16x32_bf16 v[6:9], v[182:185], v[234:237], v[6:9]
	v_mfma_f32_16x16x32_bf16 v[2:5], v[190:193], v[234:237], v[2:5]
	s_setprio 0
	s_barrier
	s_branch .Lpeel_mid_190

; #define PG8_STAGE(bufoff, gbase, voff) do { _Pragma("unroll") for (int _i = 0; _i < 2; ++_i) \
;         __builtin_amdgcn_global_load_lds((const unsigned*)((const char*)(gbase) + (voff)[_i]), (PG8_LAS unsigned*)(lds + (bufoff) + ldsw + _i * 8192), 16, 0, 0); } while (0)
; #define PG8_LDA(dst, b, h) do { _Pragma("unroll") for (int m = 0; m < 4; ++m) _Pragma("unroll") for (int k = 0; k < 2; ++k) dst[m][k] = *(const PG8_LAS bf16x8*)(lds + PG8_SA(b, h) + aoff + m * 2048 + k * 1024); } while (0)
; #define PG8_LDB(dst, b, h) do { _Pragma("unroll") for (int n = 0; n < 2; ++n) _Pragma("unroll") for (int k = 0; k < 2; ++k) dst[n][k] = *(const PG8_LAS bf16x8*)(lds + PG8_SB(b, h) + boff + n * 2048 + k * 1024); } while (0)
; #define PG8_MMA(ai, bj, At, Bt) do { __builtin_amdgcn_s_setprio(1); _Pragma("unroll") for (int m = 0; m < 4; ++m) _Pragma("unroll") for (int n = 0; n < 2; ++n) _Pragma("unroll") for (int k = 0; k < 2; ++k) \
;         acc[ai][bj][m][n] = __builtin_amdgcn_mfma_f32_16x16x32_bf16(Bt[n][k], At[m][k], acc[ai][bj][m][n], 0, 0, 0); __builtin_amdgcn_s_setprio(0); } while (0)
; #define PG8_WAIT_V(n) asm volatile("s_waitcnt vmcnt(" #n ")" ::: "memory")
; #define PG8_WAIT_L(n) asm volatile("s_waitcnt lgkmcnt(" #n ")" ::: "memory")
; template <class Epi, class Sched, bool ALIGN_EPI = false, bool SP2 = false, bool PAIR_ACC = false>
; __device__ __forceinline__ void gemm_phase(PG8_LAS unsigned char* lds, const Gemm g, const Sched& S, const Epi& E) {
;     ...
;         const char* nA = has_next ? (const char*)g.A + (size_t)nxt.pm * tstep + (size_t)(nxt.pn / g.a_div) * g.a_sel : cA; const char* nB = has_next ? (const char*)g.Bt + (size_t)nxt.pn * tstep : cB;
;         for (int t = 0; t < nt; t += 2) {
;             const bool last = (t == nt - 2);
;             const char* a1 = cA + (size_t)(t + 1) * kstep;
;             const char* a2 = last ? nA : cA + (size_t)(t + 2) * kstep; const char* b2 = last ? nB : cB + (size_t)(t + 2) * kstep;
;             const char* a3 = a2 + kstep; const char* b3 = b2 + kstep;
;             if (last && has_next) S.a_ready(nxt);
;             if constexpr (SP2) {
;             PG8_LDB(B0, 0, 0); PG8_LDB(B1, 0, 1); PG8_SCHED; PG8_LDA(At, 0, 0); PG8_STAGE(PG8_SA(1, 1), a1 + hstep, voffA);
;             PG8_WAIT_V(8); PG8_WAIT_L(0); PG8_BAR; PG8_MMA(0, 0, At, B0); PG8_MMA(0, 1, At, B1); PG8_BAR; PG8_SCHED;
.LBB0_833:
	s_ashr_i32 s65, s64, 31
	s_lshl_b64 s[40:41], s[64:65], 19
	s_add_u32 s66, s4, s40
	s_addc_u32 s67, s5, s41
	s_and_b64 s[40:41], s[8:9], exec
	s_cselect_b32 s40, s67, s11
	s_cselect_b32 s41, s66, s10
	s_ashr_i32 s63, s62, 31
	s_lshl_b64 s[68:69], s[62:63], 19
	s_add_u32 s68, s23, s68
	s_addc_u32 s69, s24, s69
	s_and_b64 s[72:73], s[8:9], exec
	s_cselect_b32 s63, s69, s39
	s_cselect_b32 s65, s68, s38
	s_add_u32 s10, s10, 0x40080
	s_addc_u32 s11, s11, 0
	s_add_u32 s78, s38, 0x100
	s_addc_u32 s79, s39, 0
	s_mov_b32 s80, -2
	ds_read_b128 v[74:77], v197
	ds_read_b128 v[78:81], v197 offset:1024
	ds_read_b128 v[82:85], v197 offset:2048
	ds_read_b128 v[86:89], v197 offset:3072
	ds_read_b128 v[90:93], v198
	ds_read_b128 v[94:97], v198 offset:1024
	ds_read_b128 v[98:101], v198 offset:2048
	ds_read_b128 v[106:109], v198 offset:3072
	s_add_u32 s38, s10, 0xfffc0080
	s_addc_u32 s39, s11, -1
	s_cmp_eq_u32 s80, 12
	s_cselect_b32 s73, s40, s39
	s_cselect_b32 s72, s41, s38
	s_cselect_b32 s39, s63, s79
	s_cselect_b32 s38, s65, s78
	v_lshl_add_u64 v[170:171], s[10:11], 0, v[186:187]
	s_add_i32 m0, s36, 0xc000
	ds_read_b128 v[162:165], v199
	ds_read_b128 v[166:169], v199 offset:1024
	ds_read_b128 v[210:213], v199 offset:2048
	ds_read_b128 v[214:217], v199 offset:3072
	ds_read_b128 v[218:221], v199 offset:4096
	ds_read_b128 v[222:225], v199 offset:5120
	ds_read_b128 v[226:229], v199 offset:6144
	ds_read_b128 v[230:233], v199 offset:7168
	global_load_lds_dwordx4 v[170:171], off
	v_lshl_add_u64 v[170:171], s[10:11], 0, v[188:189]
	s_add_i32 m0, s36, 0xe000
	s_nop 0
	global_load_lds_dwordx4 v[170:171], off
	s_waitcnt vmcnt(8)
	s_waitcnt lgkmcnt(0)
	s_barrier
	s_setprio 1
	s_waitcnt lgkmcnt(0)
	v_mfma_f32_16x16x32_bf16 v[150:153], v[74:77], v[162:165], 0
	v_mfma_f32_16x16x32_bf16 v[146:149], v[82:85], v[162:165], 0
	v_mfma_f32_16x16x32_bf16 v[134:137], v[74:77], v[210:213], 0
	v_mfma_f32_16x16x32_bf16 v[130:133], v[82:85], v[210:213], 0
	v_mfma_f32_16x16x32_bf16 v[118:121], v[74:77], v[218:221], 0
	v_mfma_f32_16x16x32_bf16 v[110:113], v[82:85], v[218:221], 0
	v_mfma_f32_16x16x32_bf16 v[114:117], v[74:77], v[226:229], 0
	v_mfma_f32_16x16x32_bf16 v[102:105], v[82:85], v[226:229], 0
	v_mfma_f32_16x16x32_bf16 v[150:153], v[78:81], v[166:169], v[150:153]
	v_mfma_f32_16x16x32_bf16 v[146:149], v[86:89], v[166:169], v[146:149]
	v_mfma_f32_16x16x32_bf16 v[134:137], v[78:81], v[214:217], v[134:137]
	v_mfma_f32_16x16x32_bf16 v[130:133], v[86:89], v[214:217], v[130:133]
	v_mfma_f32_16x16x32_bf16 v[118:121], v[78:81], v[222:225], v[118:121]
	v_mfma_f32_16x16x32_bf16 v[110:113], v[86:89], v[222:225], v[110:113]
	v_mfma_f32_16x16x32_bf16 v[114:117], v[78:81], v[230:233], v[114:117]
	v_mfma_f32_16x16x32_bf16 v[102:105], v[86:89], v[230:233], v[102:105]
	s_setprio 0
	s_setprio 1
	v_mfma_f32_16x16x32_bf16 v[158:161], v[90:93], v[162:165], 0
	v_mfma_f32_16x16x32_bf16 v[154:157], v[98:101], v[162:165], 0
	v_mfma_f32_16x16x32_bf16 v[142:145], v[90:93], v[210:213], 0
	v_mfma_f32_16x16x32_bf16 v[138:141], v[98:101], v[210:213], 0
	v_mfma_f32_16x16x32_bf16 v[126:129], v[90:93], v[218:221], 0
	v_mfma_f32_16x16x32_bf16 v[122:125], v[98:101], v[218:221], 0
	v_mfma_f32_16x16x32_bf16 v[70:73], v[90:93], v[226:229], 0
	v_mfma_f32_16x16x32_bf16 v[66:69], v[98:101], v[226:229], 0
	v_mfma_f32_16x16x32_bf16 v[158:161], v[94:97], v[166:169], v[158:161]
	v_mfma_f32_16x16x32_bf16 v[154:157], v[106:109], v[166:169], v[154:157]
	v_mfma_f32_16x16x32_bf16 v[142:145], v[94:97], v[214:217], v[142:145]
	v_mfma_f32_16x16x32_bf16 v[138:141], v[106:109], v[214:217], v[138:141]
	v_mfma_f32_16x16x32_bf16 v[126:129], v[94:97], v[222:225], v[126:129]
	v_mfma_f32_16x16x32_bf16 v[122:125], v[106:109], v[222:225], v[122:125]
	v_mfma_f32_16x16x32_bf16 v[70:73], v[94:97], v[230:233], v[70:73]
	v_mfma_f32_16x16x32_bf16 v[66:69], v[106:109], v[230:233], v[66:69]
	s_setprio 0
	s_barrier
; #define PG8_STAGE(bufoff, gbase, voff) do { _Pragma("unroll") for (int _i = 0; _i < 2; ++_i) \
;         __builtin_amdgcn_global_load_lds((const unsigned*)((const char*)(gbase) + (voff)[_i]), (PG8_LAS unsigned*)(lds + (bufoff) + ldsw + _i * 8192), 16, 0, 0); } while (0)
; #define PG8_LDA(dst, b, h) do { _Pragma("unroll") for (int m = 0; m < 4; ++m) _Pragma("unroll") for (int k = 0; k < 2; ++k) dst[m][k] = *(const PG8_LAS bf16x8*)(lds + PG8_SA(b, h) + aoff + m * 2048 + k * 1024); } while (0)
; #define PG8_MMA(ai, bj, At, Bt) do { __builtin_amdgcn_s_setprio(1); _Pragma("unroll") for (int m = 0; m < 4; ++m) _Pragma("unroll") for (int n = 0; n < 2; ++n) _Pragma("unroll") for (int k = 0; k < 2; ++k) \
;         acc[ai][bj][m][n] = __builtin_amdgcn_mfma_f32_16x16x32_bf16(Bt[n][k], At[m][k], acc[ai][bj][m][n], 0, 0, 0); __builtin_amdgcn_s_setprio(0); } while (0)
; #define PG8_WAIT_V(n) asm volatile("s_waitcnt vmcnt(" #n ")" ::: "memory")
; #define PG8_WAIT_L(n) asm volatile("s_waitcnt lgkmcnt(" #n ")" ::: "memory")
; #define PG8_BAR __builtin_amdgcn_s_barrier()
; #define PG8_SCHED __builtin_amdgcn_sched_barrier(0)
; template <class Epi, class Sched, bool ALIGN_EPI = false, bool SP2 = false, bool PAIR_ACC = false>
; __device__ __forceinline__ void gemm_phase(PG8_LAS unsigned char* lds, const Gemm g, const Sched& S, const Epi& E) {
;     ...
;             PG8_LDA(At, 0, 1); PG8_STAGE(PG8_SB(0, 0), b2, voffB); PG8_STAGE(PG8_SB(0, 1), b2 + hstep, voffB); PG8_STAGE(PG8_SA(0, 0), a2, voffA);
;             PG8_WAIT_V(8); PG8_WAIT_L(0); PG8_BAR; PG8_MMA(1, 0, At, B0); PG8_MMA(1, 1, At, B1); PG8_BAR; PG8_SCHED;
	s_add_i32 s81, s61, s25
	v_lshl_add_u64 v[170:171], s[38:39], 0, v[178:179]
	s_mov_b32 m0, s81
	ds_read_b128 v[162:165], v199 offset:16384
	ds_read_b128 v[166:169], v199 offset:17408
	ds_read_b128 v[210:213], v199 offset:18432
	ds_read_b128 v[214:217], v199 offset:19456
	ds_read_b128 v[218:221], v199 offset:20480
	ds_read_b128 v[222:225], v199 offset:21504
	ds_read_b128 v[226:229], v199 offset:22528
	ds_read_b128 v[230:233], v199 offset:23552
	global_load_lds_dwordx4 v[170:171], off
	s_add_i32 m0, s81, 0x2000
	s_add_u32 s82, s38, 0x40000
	v_lshl_add_u64 v[194:195], s[38:39], 0, v[174:175]
	s_addc_u32 s83, s39, 0
	s_add_i32 s81, s74, s25
	global_load_lds_dwordx4 v[194:195], off
	v_lshl_add_u64 v[234:235], s[82:83], 0, v[178:179]
	s_mov_b32 m0, s81
	v_lshl_add_u64 v[236:237], s[72:73], 0, v[176:177]
	global_load_lds_dwordx4 v[234:235], off
	v_lshl_add_u64 v[234:235], s[82:83], 0, v[174:175]
	s_add_i32 m0, s81, 0x2000
	s_nop 0
	global_load_lds_dwordx4 v[234:235], off
	v_lshl_add_u64 v[234:235], s[72:73], 0, v[180:181]
	s_mov_b32 m0, s36
	s_nop 0
	global_load_lds_dwordx4 v[234:235], off
	s_mov_b32 m0, s37
	s_nop 0
	global_load_lds_dwordx4 v[236:237], off
	s_waitcnt vmcnt(8)
	s_waitcnt lgkmcnt(0)
	s_barrier
	s_setprio 1
	s_waitcnt lgkmcnt(0)
	v_mfma_f32_16x16x32_bf16 v[54:57], v[74:77], v[162:165], 0
	v_mfma_f32_16x16x32_bf16 v[50:53], v[82:85], v[162:165], 0
	v_mfma_f32_16x16x32_bf16 v[38:41], v[74:77], v[210:213], 0
	v_mfma_f32_16x16x32_bf16 v[34:37], v[82:85], v[210:213], 0
	v_mfma_f32_16x16x32_bf16 v[22:25], v[74:77], v[218:221], 0
	v_mfma_f32_16x16x32_bf16 v[14:17], v[82:85], v[218:221], 0
	v_mfma_f32_16x16x32_bf16 v[18:21], v[74:77], v[226:229], 0
	v_mfma_f32_16x16x32_bf16 v[10:13], v[82:85], v[226:229], 0
	v_mfma_f32_16x16x32_bf16 v[54:57], v[78:81], v[166:169], v[54:57]
	v_mfma_f32_16x16x32_bf16 v[50:53], v[86:89], v[166:169], v[50:53]
	v_mfma_f32_16x16x32_bf16 v[38:41], v[78:81], v[214:217], v[38:41]
	v_mfma_f32_16x16x32_bf16 v[34:37], v[86:89], v[214:217], v[34:37]
	v_mfma_f32_16x16x32_bf16 v[22:25], v[78:81], v[222:225], v[22:25]
	v_mfma_f32_16x16x32_bf16 v[14:17], v[86:89], v[222:225], v[14:17]
	v_mfma_f32_16x16x32_bf16 v[18:21], v[78:81], v[230:233], v[18:21]
	v_mfma_f32_16x16x32_bf16 v[10:13], v[86:89], v[230:233], v[10:13]
	s_setprio 0
	s_setprio 1
	v_mfma_f32_16x16x32_bf16 v[62:65], v[90:93], v[162:165], 0
	v_mfma_f32_16x16x32_bf16 v[58:61], v[98:101], v[162:165], 0
	v_mfma_f32_16x16x32_bf16 v[46:49], v[90:93], v[210:213], 0
	v_mfma_f32_16x16x32_bf16 v[42:45], v[98:101], v[210:213], 0
	v_mfma_f32_16x16x32_bf16 v[30:33], v[90:93], v[218:221], 0
	v_mfma_f32_16x16x32_bf16 v[26:29], v[98:101], v[218:221], 0
	v_mfma_f32_16x16x32_bf16 v[6:9], v[90:93], v[226:229], 0
	v_mfma_f32_16x16x32_bf16 v[2:5], v[98:101], v[226:229], 0
	v_mfma_f32_16x16x32_bf16 v[62:65], v[94:97], v[166:169], v[62:65]
	v_mfma_f32_16x16x32_bf16 v[58:61], v[106:109], v[166:169], v[58:61]
	v_mfma_f32_16x16x32_bf16 v[46:49], v[94:97], v[214:217], v[46:49]
	v_mfma_f32_16x16x32_bf16 v[42:45], v[106:109], v[214:217], v[42:45]
	v_mfma_f32_16x16x32_bf16 v[30:33], v[94:97], v[222:225], v[30:33]
	v_mfma_f32_16x16x32_bf16 v[26:29], v[106:109], v[222:225], v[26:29]
	v_mfma_f32_16x16x32_bf16 v[6:9], v[94:97], v[230:233], v[6:9]
	v_mfma_f32_16x16x32_bf16 v[2:5], v[106:109], v[230:233], v[2:5]
	s_setprio 0
	s_barrier
	s_branch .Lpeel_mid_834

; #define PG8_STAGE(bufoff, gbase, voff) do { _Pragma("unroll") for (int _i = 0; _i < 2; ++_i) \
;         __builtin_amdgcn_global_load_lds((const unsigned*)((const char*)(gbase) + (voff)[_i]), (PG8_LAS unsigned*)(lds + (bufoff) + ldsw + _i * 8192), 16, 0, 0); } while (0)
; #define PG8_LDA(dst, b, h) do { _Pragma("unroll") for (int m = 0; m < 4; ++m) _Pragma("unroll") for (int k = 0; k < 2; ++k) dst[m][k] = *(const PG8_LAS bf16x8*)(lds + PG8_SA(b, h) + aoff + m * 2048 + k * 1024); } while (0)
; #define PG8_LDB(dst, b, h) do { _Pragma("unroll") for (int n = 0; n < 2; ++n) _Pragma("unroll") for (int k = 0; k < 2; ++k) dst[n][k] = *(const PG8_LAS bf16x8*)(lds + PG8_SB(b, h) + boff + n * 2048 + k * 1024); } while (0)
; #define PG8_MMA(ai, bj, At, Bt) do { __builtin_amdgcn_s_setprio(1); _Pragma("unroll") for (int m = 0; m < 4; ++m) _Pragma("unroll") for (int n = 0; n < 2; ++n) _Pragma("unroll") for (int k = 0; k < 2; ++k) \
;         acc[ai][bj][m][n] = __builtin_amdgcn_mfma_f32_16x16x32_bf16(Bt[n][k], At[m][k], acc[ai][bj][m][n], 0, 0, 0); __builtin_amdgcn_s_setprio(0); } while (0)
; #define PG8_WAIT_V(n) asm volatile("s_waitcnt vmcnt(" #n ")" ::: "memory")
; #define PG8_WAIT_L(n) asm volatile("s_waitcnt lgkmcnt(" #n ")" ::: "memory")
; template <class Epi, class Sched, bool ALIGN_EPI = false, bool SP2 = false, bool PAIR_ACC = false>
; __device__ __forceinline__ void gemm_phase(PG8_LAS unsigned char* lds, const Gemm g, const Sched& S, const Epi& E) {
;     ...
;         const char* nA = has_next ? (const char*)g.A + (size_t)nxt.pm * tstep + (size_t)(nxt.pn / g.a_div) * g.a_sel : cA; const char* nB = has_next ? (const char*)g.Bt + (size_t)nxt.pn * tstep : cB;
;         for (int t = 0; t < nt; t += 2) {
;             const bool last = (t == nt - 2);
;             const char* a1 = cA + (size_t)(t + 1) * kstep;
;             const char* a2 = last ? nA : cA + (size_t)(t + 2) * kstep; const char* b2 = last ? nB : cB + (size_t)(t + 2) * kstep;
;             const char* a3 = a2 + kstep; const char* b3 = b2 + kstep;
;             if (last && has_next) S.a_ready(nxt);
;             if constexpr (SP2) {
;             PG8_LDB(B0, 0, 0); PG8_LDB(B1, 0, 1); PG8_SCHED; PG8_LDA(At, 0, 0); PG8_STAGE(PG8_SA(1, 1), a1 + hstep, voffA);
;             PG8_WAIT_V(8); PG8_WAIT_L(0); PG8_BAR; PG8_MMA(0, 0, At, B0); PG8_MMA(0, 1, At, B1); PG8_BAR; PG8_SCHED;
.LBB0_1092:
	s_mov_b32 s78, s23
	s_ashr_i32 s79, s23, 31
	s_lshl_b64 s[20:21], s[78:79], 19
	s_add_u32 s82, s59, s20
	s_addc_u32 s83, s61, s21
	s_mov_b32 s76, s19
	s_and_b64 s[20:21], s[80:81], exec
	s_cselect_b32 s15, s83, s13
	s_cselect_b32 s19, s82, s12
	s_ashr_i32 s77, s76, 31
	s_lshl_b64 s[20:21], s[76:77], 19
	s_add_u32 s84, s63, s20
	s_addc_u32 s85, s69, s21
	s_and_b64 s[20:21], s[80:81], exec
	s_cselect_b32 s22, s85, s17
	s_cselect_b32 s23, s84, s16
	s_add_u32 s12, s12, 0x40080
	s_addc_u32 s13, s13, 0
	s_add_u32 s30, s16, 0x100
	s_addc_u32 s42, s17, 0
	s_mov_b32 s43, -2
	s_waitcnt lgkmcnt(0)
	ds_read_b128 v[130:133], v195
	ds_read_b128 v[134:137], v195 offset:1024
	ds_read_b128 v[138:141], v195 offset:2048
	ds_read_b128 v[142:145], v195 offset:3072
	ds_read_b128 v[176:179], v196
	ds_read_b128 v[180:183], v196 offset:1024
	ds_read_b128 v[184:187], v196 offset:2048
	ds_read_b128 v[188:191], v196 offset:3072
	s_add_u32 s16, s12, 0xfffc0080
	s_addc_u32 s17, s13, -1
	s_cmp_eq_u32 s43, 12
	s_cselect_b32 s21, s15, s17
	s_cselect_b32 s20, s19, s16
	s_cselect_b32 s17, s22, s42
	s_cselect_b32 s16, s23, s30
	v_lshl_add_u64 v[192:193], s[12:13], 0, v[170:171]
	s_add_i32 m0, s73, 0xc000
	ds_read_b128 v[200:203], v197
	ds_read_b128 v[204:207], v197 offset:1024
	ds_read_b128 v[208:211], v197 offset:2048
	ds_read_b128 v[212:215], v197 offset:3072
	ds_read_b128 v[216:219], v197 offset:4096
	ds_read_b128 v[220:223], v197 offset:5120
	ds_read_b128 v[224:227], v197 offset:6144
	ds_read_b128 v[228:231], v197 offset:7168
	global_load_lds_dwordx4 v[192:193], off
	v_lshl_add_u64 v[192:193], s[12:13], 0, v[172:173]
	s_add_i32 m0, s73, 0xe000
	s_nop 0
	global_load_lds_dwordx4 v[192:193], off
	s_waitcnt vmcnt(8)
	s_waitcnt lgkmcnt(0)
	s_barrier
	s_setprio 1
	s_waitcnt lgkmcnt(0)
	v_mfma_f32_16x16x32_bf16 v[126:129], v[130:133], v[200:203], 0
	v_mfma_f32_16x16x32_bf16 v[122:125], v[138:141], v[200:203], 0
	v_mfma_f32_16x16x32_bf16 v[110:113], v[130:133], v[208:211], 0
	v_mfma_f32_16x16x32_bf16 v[106:109], v[138:141], v[208:211], 0
	v_mfma_f32_16x16x32_bf16 v[94:97], v[130:133], v[216:219], 0
	v_mfma_f32_16x16x32_bf16 v[90:93], v[138:141], v[216:219], 0
	v_mfma_f32_16x16x32_bf16 v[78:81], v[130:133], v[224:227], 0
	v_mfma_f32_16x16x32_bf16 v[74:77], v[138:141], v[224:227], 0
	v_mfma_f32_16x16x32_bf16 v[126:129], v[134:137], v[204:207], v[126:129]
	v_mfma_f32_16x16x32_bf16 v[122:125], v[142:145], v[204:207], v[122:125]
	v_mfma_f32_16x16x32_bf16 v[110:113], v[134:137], v[212:215], v[110:113]
	v_mfma_f32_16x16x32_bf16 v[106:109], v[142:145], v[212:215], v[106:109]
	v_mfma_f32_16x16x32_bf16 v[94:97], v[134:137], v[220:223], v[94:97]
	v_mfma_f32_16x16x32_bf16 v[90:93], v[142:145], v[220:223], v[90:93]
	v_mfma_f32_16x16x32_bf16 v[78:81], v[134:137], v[228:231], v[78:81]
	v_mfma_f32_16x16x32_bf16 v[74:77], v[142:145], v[228:231], v[74:77]
	s_setprio 0
	s_setprio 1
	v_mfma_f32_16x16x32_bf16 v[118:121], v[176:179], v[200:203], 0
	v_mfma_f32_16x16x32_bf16 v[114:117], v[184:187], v[200:203], 0
	v_mfma_f32_16x16x32_bf16 v[102:105], v[176:179], v[208:211], 0
	v_mfma_f32_16x16x32_bf16 v[98:101], v[184:187], v[208:211], 0
	v_mfma_f32_16x16x32_bf16 v[86:89], v[176:179], v[216:219], 0
	v_mfma_f32_16x16x32_bf16 v[82:85], v[184:187], v[216:219], 0
	v_mfma_f32_16x16x32_bf16 v[70:73], v[176:179], v[224:227], 0
	v_mfma_f32_16x16x32_bf16 v[66:69], v[184:187], v[224:227], 0
	v_mfma_f32_16x16x32_bf16 v[118:121], v[180:183], v[204:207], v[118:121]
	v_mfma_f32_16x16x32_bf16 v[114:117], v[188:191], v[204:207], v[114:117]
	v_mfma_f32_16x16x32_bf16 v[102:105], v[180:183], v[212:215], v[102:105]
	v_mfma_f32_16x16x32_bf16 v[98:101], v[188:191], v[212:215], v[98:101]
	v_mfma_f32_16x16x32_bf16 v[86:89], v[180:183], v[220:223], v[86:89]
	v_mfma_f32_16x16x32_bf16 v[82:85], v[188:191], v[220:223], v[82:85]
	v_mfma_f32_16x16x32_bf16 v[70:73], v[180:183], v[228:231], v[70:73]
	v_mfma_f32_16x16x32_bf16 v[66:69], v[188:191], v[228:231], v[66:69]
	s_setprio 0
	s_barrier
; #define PG8_STAGE(bufoff, gbase, voff) do { _Pragma("unroll") for (int _i = 0; _i < 2; ++_i) \
;         __builtin_amdgcn_global_load_lds((const unsigned*)((const char*)(gbase) + (voff)[_i]), (PG8_LAS unsigned*)(lds + (bufoff) + ldsw + _i * 8192), 16, 0, 0); } while (0)
; #define PG8_LDA(dst, b, h) do { _Pragma("unroll") for (int m = 0; m < 4; ++m) _Pragma("unroll") for (int k = 0; k < 2; ++k) dst[m][k] = *(const PG8_LAS bf16x8*)(lds + PG8_SA(b, h) + aoff + m * 2048 + k * 1024); } while (0)
; #define PG8_MMA(ai, bj, At, Bt) do { __builtin_amdgcn_s_setprio(1); _Pragma("unroll") for (int m = 0; m < 4; ++m) _Pragma("unroll") for (int n = 0; n < 2; ++n) _Pragma("unroll") for (int k = 0; k < 2; ++k) \
;         acc[ai][bj][m][n] = __builtin_amdgcn_mfma_f32_16x16x32_bf16(Bt[n][k], At[m][k], acc[ai][bj][m][n], 0, 0, 0); __builtin_amdgcn_s_setprio(0); } while (0)
; #define PG8_WAIT_V(n) asm volatile("s_waitcnt vmcnt(" #n ")" ::: "memory")
; #define PG8_WAIT_L(n) asm volatile("s_waitcnt lgkmcnt(" #n ")" ::: "memory")
; #define PG8_BAR __builtin_amdgcn_s_barrier()
; #define PG8_SCHED __builtin_amdgcn_sched_barrier(0)
; template <class Epi, class Sched, bool ALIGN_EPI = false, bool SP2 = false, bool PAIR_ACC = false>
; __device__ __forceinline__ void gemm_phase(PG8_LAS unsigned char* lds, const Gemm g, const Sched& S, const Epi& E) {
;     ...
;             PG8_LDA(At, 0, 1); PG8_STAGE(PG8_SB(0, 0), b2, voffB); PG8_STAGE(PG8_SB(0, 1), b2 + hstep, voffB); PG8_STAGE(PG8_SA(0, 0), a2, voffA);
;             PG8_WAIT_V(8); PG8_WAIT_L(0); PG8_BAR; PG8_MMA(1, 0, At, B0); PG8_MMA(1, 1, At, B1); PG8_BAR; PG8_SCHED;
	s_add_i32 s77, s34, s71
	v_lshl_add_u64 v[192:193], s[16:17], 0, v[148:149]
	s_mov_b32 m0, s77
	ds_read_b128 v[200:203], v197 offset:16384
	ds_read_b128 v[204:207], v197 offset:17408
	ds_read_b128 v[208:211], v197 offset:18432
	ds_read_b128 v[212:215], v197 offset:19456
	ds_read_b128 v[216:219], v197 offset:20480
	ds_read_b128 v[220:223], v197 offset:21504
	ds_read_b128 v[224:227], v197 offset:22528
	ds_read_b128 v[228:231], v197 offset:23552
	global_load_lds_dwordx4 v[192:193], off
	s_add_i32 m0, s77, 0x2000
	s_add_u32 s86, s16, 0x40000
	v_lshl_add_u64 v[232:233], s[16:17], 0, v[152:153]
	s_addc_u32 s87, s17, 0
	s_add_i32 s77, s35, s71
	global_load_lds_dwordx4 v[232:233], off
	v_lshl_add_u64 v[234:235], s[86:87], 0, v[148:149]
	s_mov_b32 m0, s77
	v_lshl_add_u64 v[236:237], s[20:21], 0, v[150:151]
	global_load_lds_dwordx4 v[234:235], off
	v_lshl_add_u64 v[234:235], s[86:87], 0, v[152:153]
	s_add_i32 m0, s77, 0x2000
	s_nop 0
	global_load_lds_dwordx4 v[234:235], off
	v_lshl_add_u64 v[234:235], s[20:21], 0, v[146:147]
	s_mov_b32 m0, s73
	s_nop 0
	global_load_lds_dwordx4 v[234:235], off
	s_mov_b32 m0, s75
	s_nop 0
	global_load_lds_dwordx4 v[236:237], off
	s_waitcnt vmcnt(8)
	s_waitcnt lgkmcnt(0)
	s_barrier
	s_setprio 1
	s_waitcnt lgkmcnt(0)
	v_mfma_f32_16x16x32_bf16 v[62:65], v[130:133], v[200:203], 0
	v_mfma_f32_16x16x32_bf16 v[58:61], v[138:141], v[200:203], 0
	v_mfma_f32_16x16x32_bf16 v[46:49], v[130:133], v[208:211], 0
	v_mfma_f32_16x16x32_bf16 v[42:45], v[138:141], v[208:211], 0
	v_mfma_f32_16x16x32_bf16 v[30:33], v[130:133], v[216:219], 0
	v_mfma_f32_16x16x32_bf16 v[26:29], v[138:141], v[216:219], 0
	v_mfma_f32_16x16x32_bf16 v[14:17], v[130:133], v[224:227], 0
	v_mfma_f32_16x16x32_bf16 v[10:13], v[138:141], v[224:227], 0
	v_mfma_f32_16x16x32_bf16 v[62:65], v[134:137], v[204:207], v[62:65]
	v_mfma_f32_16x16x32_bf16 v[58:61], v[142:145], v[204:207], v[58:61]
	v_mfma_f32_16x16x32_bf16 v[46:49], v[134:137], v[212:215], v[46:49]
	v_mfma_f32_16x16x32_bf16 v[42:45], v[142:145], v[212:215], v[42:45]
	v_mfma_f32_16x16x32_bf16 v[30:33], v[134:137], v[220:223], v[30:33]
	v_mfma_f32_16x16x32_bf16 v[26:29], v[142:145], v[220:223], v[26:29]
	v_mfma_f32_16x16x32_bf16 v[14:17], v[134:137], v[228:231], v[14:17]
	v_mfma_f32_16x16x32_bf16 v[10:13], v[142:145], v[228:231], v[10:13]
	s_setprio 0
	s_setprio 1
	v_mfma_f32_16x16x32_bf16 v[54:57], v[176:179], v[200:203], 0
	v_mfma_f32_16x16x32_bf16 v[50:53], v[184:187], v[200:203], 0
	v_mfma_f32_16x16x32_bf16 v[38:41], v[176:179], v[208:211], 0
	v_mfma_f32_16x16x32_bf16 v[34:37], v[184:187], v[208:211], 0
	v_mfma_f32_16x16x32_bf16 v[22:25], v[176:179], v[216:219], 0
	v_mfma_f32_16x16x32_bf16 v[18:21], v[184:187], v[216:219], 0
	v_mfma_f32_16x16x32_bf16 v[6:9], v[176:179], v[224:227], 0
	v_mfma_f32_16x16x32_bf16 v[2:5], v[184:187], v[224:227], 0
	v_mfma_f32_16x16x32_bf16 v[54:57], v[180:183], v[204:207], v[54:57]
	v_mfma_f32_16x16x32_bf16 v[50:53], v[188:191], v[204:207], v[50:53]
	v_mfma_f32_16x16x32_bf16 v[38:41], v[180:183], v[212:215], v[38:41]
	v_mfma_f32_16x16x32_bf16 v[34:37], v[188:191], v[212:215], v[34:37]
	v_mfma_f32_16x16x32_bf16 v[22:25], v[180:183], v[220:223], v[22:25]
	v_mfma_f32_16x16x32_bf16 v[18:21], v[188:191], v[220:223], v[18:21]
	v_mfma_f32_16x16x32_bf16 v[6:9], v[180:183], v[228:231], v[6:9]
	v_mfma_f32_16x16x32_bf16 v[2:5], v[188:191], v[228:231], v[2:5]
	s_setprio 0
	s_barrier
	s_branch .Lpeel_mid_1093

; #define PG8_STAGE(bufoff, gbase, voff) do { _Pragma("unroll") for (int _i = 0; _i < 2; ++_i) \
;         __builtin_amdgcn_global_load_lds((const unsigned*)((const char*)(gbase) + (voff)[_i]), (PG8_LAS unsigned*)(lds + (bufoff) + ldsw + _i * 8192), 16, 0, 0); } while (0)
; #define PG8_LDA(dst, b, h) do { _Pragma("unroll") for (int m = 0; m < 4; ++m) _Pragma("unroll") for (int k = 0; k < 2; ++k) dst[m][k] = *(const PG8_LAS bf16x8*)(lds + PG8_SA(b, h) + aoff + m * 2048 + k * 1024); } while (0)
; #define PG8_LDB(dst, b, h) do { _Pragma("unroll") for (int n = 0; n < 2; ++n) _Pragma("unroll") for (int k = 0; k < 2; ++k) dst[n][k] = *(const PG8_LAS bf16x8*)(lds + PG8_SB(b, h) + boff + n * 2048 + k * 1024); } while (0)
; #define PG8_MMA(ai, bj, At, Bt) do { __builtin_amdgcn_s_setprio(1); _Pragma("unroll") for (int m = 0; m < 4; ++m) _Pragma("unroll") for (int n = 0; n < 2; ++n) _Pragma("unroll") for (int k = 0; k < 2; ++k) \
;         acc[ai][bj][m][n] = __builtin_amdgcn_mfma_f32_16x16x32_bf16(Bt[n][k], At[m][k], acc[ai][bj][m][n], 0, 0, 0); __builtin_amdgcn_s_setprio(0); } while (0)
; #define PG8_WAIT_V(n) asm volatile("s_waitcnt vmcnt(" #n ")" ::: "memory")
; #define PG8_WAIT_L(n) asm volatile("s_waitcnt lgkmcnt(" #n ")" ::: "memory")
; template <class Epi, class Sched, bool ALIGN_EPI = false, bool SP2 = false, bool PAIR_ACC = false>
; __device__ __forceinline__ void gemm_phase(PG8_LAS unsigned char* lds, const Gemm g, const Sched& S, const Epi& E) {
;     ...
;         const char* nA = has_next ? (const char*)g.A + (size_t)nxt.pm * tstep + (size_t)(nxt.pn / g.a_div) * g.a_sel : cA; const char* nB = has_next ? (const char*)g.Bt + (size_t)nxt.pn * tstep : cB;
;         for (int t = 0; t < nt; t += 2) {
;             const bool last = (t == nt - 2);
;             const char* a1 = cA + (size_t)(t + 1) * kstep;
;             const char* a2 = last ? nA : cA + (size_t)(t + 2) * kstep; const char* b2 = last ? nB : cB + (size_t)(t + 2) * kstep;
;             const char* a3 = a2 + kstep; const char* b3 = b2 + kstep;
;             if (last && has_next) S.a_ready(nxt);
;             if constexpr (SP2) {
;             PG8_LDB(B0, 0, 0); PG8_LDB(B1, 0, 1); PG8_SCHED; PG8_LDA(At, 0, 0); PG8_STAGE(PG8_SA(1, 1), a1 + hstep, voffA);
;             PG8_WAIT_V(8); PG8_WAIT_L(0); PG8_BAR; PG8_MMA(0, 0, At, B0); PG8_MMA(0, 1, At, B1); PG8_BAR; PG8_SCHED;
.LBB0_1736:
	s_ashr_i32 s53, s52, 31
	s_lshl_b64 s[10:11], s[52:53], 19
	s_add_u32 s54, s4, s10
	s_addc_u32 s55, s5, s11
	s_and_b64 s[10:11], s[8:9], exec
	s_cselect_b32 s53, s55, s63
	s_cselect_b32 s75, s54, s62
	s_ashr_i32 s51, s50, 31
	s_lshl_b64 s[10:11], s[50:51], 19
	s_add_u32 s56, s24, s10
	s_addc_u32 s57, s25, s11
	s_and_b64 s[10:11], s[8:9], exec
	s_cselect_b32 s51, s57, s61
	s_cselect_b32 s76, s56, s60
	s_add_u32 s10, s62, 0x40080
	s_addc_u32 s11, s63, 0
	s_add_u32 s77, s60, 0x100
	s_addc_u32 s78, s61, 0
	s_mov_b32 s79, -2
	ds_read_b128 v[74:77], v196
	ds_read_b128 v[78:81], v196 offset:1024
	ds_read_b128 v[82:85], v196 offset:2048
	ds_read_b128 v[86:89], v196 offset:3072
	ds_read_b128 v[90:93], v197
	ds_read_b128 v[94:97], v197 offset:1024
	ds_read_b128 v[98:101], v197 offset:2048
	ds_read_b128 v[106:109], v197 offset:3072
	s_add_u32 s60, s10, 0xfffc0080
	s_addc_u32 s61, s11, -1
	s_cmp_eq_u32 s79, 12
	s_cselect_b32 s63, s53, s61
	s_cselect_b32 s62, s75, s60
	s_cselect_b32 s61, s51, s78
	s_cselect_b32 s60, s76, s77
	v_lshl_add_u64 v[170:171], s[10:11], 0, v[184:185]
	s_add_i32 m0, s36, 0xc000
	ds_read_b128 v[162:165], v198
	ds_read_b128 v[166:169], v198 offset:1024
	ds_read_b128 v[204:207], v198 offset:2048
	ds_read_b128 v[208:211], v198 offset:3072
	ds_read_b128 v[212:215], v198 offset:4096
	ds_read_b128 v[216:219], v198 offset:5120
	ds_read_b128 v[220:223], v198 offset:6144
	ds_read_b128 v[224:227], v198 offset:7168
	global_load_lds_dwordx4 v[170:171], off
	v_lshl_add_u64 v[170:171], s[10:11], 0, v[186:187]
	s_add_i32 m0, s36, 0xe000
	s_nop 0
	global_load_lds_dwordx4 v[170:171], off
	s_waitcnt vmcnt(8)
	s_waitcnt lgkmcnt(0)
	s_barrier
	s_setprio 1
	s_waitcnt lgkmcnt(0)
	v_mfma_f32_16x16x32_bf16 v[150:153], v[74:77], v[162:165], 0
	v_mfma_f32_16x16x32_bf16 v[146:149], v[82:85], v[162:165], 0
	v_mfma_f32_16x16x32_bf16 v[134:137], v[74:77], v[204:207], 0
	v_mfma_f32_16x16x32_bf16 v[130:133], v[82:85], v[204:207], 0
	v_mfma_f32_16x16x32_bf16 v[118:121], v[74:77], v[212:215], 0
	v_mfma_f32_16x16x32_bf16 v[110:113], v[82:85], v[212:215], 0
	v_mfma_f32_16x16x32_bf16 v[114:117], v[74:77], v[220:223], 0
	v_mfma_f32_16x16x32_bf16 v[102:105], v[82:85], v[220:223], 0
	v_mfma_f32_16x16x32_bf16 v[150:153], v[78:81], v[166:169], v[150:153]
	v_mfma_f32_16x16x32_bf16 v[146:149], v[86:89], v[166:169], v[146:149]
	v_mfma_f32_16x16x32_bf16 v[134:137], v[78:81], v[208:211], v[134:137]
	v_mfma_f32_16x16x32_bf16 v[130:133], v[86:89], v[208:211], v[130:133]
	v_mfma_f32_16x16x32_bf16 v[118:121], v[78:81], v[216:219], v[118:121]
	v_mfma_f32_16x16x32_bf16 v[110:113], v[86:89], v[216:219], v[110:113]
	v_mfma_f32_16x16x32_bf16 v[114:117], v[78:81], v[224:227], v[114:117]
	v_mfma_f32_16x16x32_bf16 v[102:105], v[86:89], v[224:227], v[102:105]
	s_setprio 0
	s_setprio 1
	v_mfma_f32_16x16x32_bf16 v[158:161], v[90:93], v[162:165], 0
	v_mfma_f32_16x16x32_bf16 v[154:157], v[98:101], v[162:165], 0
	v_mfma_f32_16x16x32_bf16 v[142:145], v[90:93], v[204:207], 0
	v_mfma_f32_16x16x32_bf16 v[138:141], v[98:101], v[204:207], 0
	v_mfma_f32_16x16x32_bf16 v[126:129], v[90:93], v[212:215], 0
	v_mfma_f32_16x16x32_bf16 v[122:125], v[98:101], v[212:215], 0
	v_mfma_f32_16x16x32_bf16 v[70:73], v[90:93], v[220:223], 0
	v_mfma_f32_16x16x32_bf16 v[66:69], v[98:101], v[220:223], 0
	v_mfma_f32_16x16x32_bf16 v[158:161], v[94:97], v[166:169], v[158:161]
	v_mfma_f32_16x16x32_bf16 v[154:157], v[106:109], v[166:169], v[154:157]
	v_mfma_f32_16x16x32_bf16 v[142:145], v[94:97], v[208:211], v[142:145]
	v_mfma_f32_16x16x32_bf16 v[138:141], v[106:109], v[208:211], v[138:141]
	v_mfma_f32_16x16x32_bf16 v[126:129], v[94:97], v[216:219], v[126:129]
	v_mfma_f32_16x16x32_bf16 v[122:125], v[106:109], v[216:219], v[122:125]
	v_mfma_f32_16x16x32_bf16 v[70:73], v[94:97], v[224:227], v[70:73]
	v_mfma_f32_16x16x32_bf16 v[66:69], v[106:109], v[224:227], v[66:69]
	s_setprio 0
	s_barrier
; #define PG8_STAGE(bufoff, gbase, voff) do { _Pragma("unroll") for (int _i = 0; _i < 2; ++_i) \
;         __builtin_amdgcn_global_load_lds((const unsigned*)((const char*)(gbase) + (voff)[_i]), (PG8_LAS unsigned*)(lds + (bufoff) + ldsw + _i * 8192), 16, 0, 0); } while (0)
; #define PG8_LDA(dst, b, h) do { _Pragma("unroll") for (int m = 0; m < 4; ++m) _Pragma("unroll") for (int k = 0; k < 2; ++k) dst[m][k] = *(const PG8_LAS bf16x8*)(lds + PG8_SA(b, h) + aoff + m * 2048 + k * 1024); } while (0)
; #define PG8_MMA(ai, bj, At, Bt) do { __builtin_amdgcn_s_setprio(1); _Pragma("unroll") for (int m = 0; m < 4; ++m) _Pragma("unroll") for (int n = 0; n < 2; ++n) _Pragma("unroll") for (int k = 0; k < 2; ++k) \
;         acc[ai][bj][m][n] = __builtin_amdgcn_mfma_f32_16x16x32_bf16(Bt[n][k], At[m][k], acc[ai][bj][m][n], 0, 0, 0); __builtin_amdgcn_s_setprio(0); } while (0)
; #define PG8_WAIT_V(n) asm volatile("s_waitcnt vmcnt(" #n ")" ::: "memory")
; #define PG8_WAIT_L(n) asm volatile("s_waitcnt lgkmcnt(" #n ")" ::: "memory")
; #define PG8_BAR __builtin_amdgcn_s_barrier()
; #define PG8_SCHED __builtin_amdgcn_sched_barrier(0)
; template <class Epi, class Sched, bool ALIGN_EPI = false, bool SP2 = false, bool PAIR_ACC = false>
; __device__ __forceinline__ void gemm_phase(PG8_LAS unsigned char* lds, const Gemm g, const Sched& S, const Epi& E) {
;     ...
;             PG8_LDA(At, 0, 1); PG8_STAGE(PG8_SB(0, 0), b2, voffB); PG8_STAGE(PG8_SB(0, 1), b2 + hstep, voffB); PG8_STAGE(PG8_SA(0, 0), a2, voffA);
;             PG8_WAIT_V(8); PG8_WAIT_L(0); PG8_BAR; PG8_MMA(1, 0, At, B0); PG8_MMA(1, 1, At, B1); PG8_BAR; PG8_SCHED;
	s_add_i32 s80, s70, s34
	v_lshl_add_u64 v[170:171], s[60:61], 0, v[176:177]
	s_mov_b32 m0, s80
	ds_read_b128 v[162:165], v198 offset:16384
	ds_read_b128 v[166:169], v198 offset:17408
	ds_read_b128 v[204:207], v198 offset:18432
	ds_read_b128 v[208:211], v198 offset:19456
	ds_read_b128 v[212:215], v198 offset:20480
	ds_read_b128 v[216:219], v198 offset:21504
	ds_read_b128 v[220:223], v198 offset:22528
	ds_read_b128 v[224:227], v198 offset:23552
	global_load_lds_dwordx4 v[170:171], off
	s_add_i32 m0, s80, 0x2000
	s_add_u32 s80, s60, 0x40000
	v_lshl_add_u64 v[192:193], s[60:61], 0, v[172:173]
	s_addc_u32 s81, s61, 0
	s_add_i32 s82, s71, s34
	global_load_lds_dwordx4 v[192:193], off
	v_lshl_add_u64 v[228:229], s[80:81], 0, v[176:177]
	s_mov_b32 m0, s82
	v_lshl_add_u64 v[230:231], s[62:63], 0, v[174:175]
	global_load_lds_dwordx4 v[228:229], off
	v_lshl_add_u64 v[228:229], s[80:81], 0, v[172:173]
	s_add_i32 m0, s82, 0x2000
	s_nop 0
	global_load_lds_dwordx4 v[228:229], off
	v_lshl_add_u64 v[228:229], s[62:63], 0, v[178:179]
	s_mov_b32 m0, s36
	s_nop 0
	global_load_lds_dwordx4 v[228:229], off
	s_mov_b32 m0, s37
	s_nop 0
	global_load_lds_dwordx4 v[230:231], off
	s_waitcnt vmcnt(8)
	s_waitcnt lgkmcnt(0)
	s_barrier
	s_setprio 1
	s_waitcnt lgkmcnt(0)
	v_mfma_f32_16x16x32_bf16 v[54:57], v[74:77], v[162:165], 0
	v_mfma_f32_16x16x32_bf16 v[50:53], v[82:85], v[162:165], 0
	v_mfma_f32_16x16x32_bf16 v[38:41], v[74:77], v[204:207], 0
	v_mfma_f32_16x16x32_bf16 v[34:37], v[82:85], v[204:207], 0
	v_mfma_f32_16x16x32_bf16 v[22:25], v[74:77], v[212:215], 0
	v_mfma_f32_16x16x32_bf16 v[14:17], v[82:85], v[212:215], 0
	v_mfma_f32_16x16x32_bf16 v[18:21], v[74:77], v[220:223], 0
	v_mfma_f32_16x16x32_bf16 v[10:13], v[82:85], v[220:223], 0
	v_mfma_f32_16x16x32_bf16 v[54:57], v[78:81], v[166:169], v[54:57]
	v_mfma_f32_16x16x32_bf16 v[50:53], v[86:89], v[166:169], v[50:53]
	v_mfma_f32_16x16x32_bf16 v[38:41], v[78:81], v[208:211], v[38:41]
	v_mfma_f32_16x16x32_bf16 v[34:37], v[86:89], v[208:211], v[34:37]
	v_mfma_f32_16x16x32_bf16 v[22:25], v[78:81], v[216:219], v[22:25]
	v_mfma_f32_16x16x32_bf16 v[14:17], v[86:89], v[216:219], v[14:17]
	v_mfma_f32_16x16x32_bf16 v[18:21], v[78:81], v[224:227], v[18:21]
	v_mfma_f32_16x16x32_bf16 v[10:13], v[86:89], v[224:227], v[10:13]
	s_setprio 0
	s_setprio 1
	v_mfma_f32_16x16x32_bf16 v[62:65], v[90:93], v[162:165], 0
	v_mfma_f32_16x16x32_bf16 v[58:61], v[98:101], v[162:165], 0
	v_mfma_f32_16x16x32_bf16 v[46:49], v[90:93], v[204:207], 0
	v_mfma_f32_16x16x32_bf16 v[42:45], v[98:101], v[204:207], 0
	v_mfma_f32_16x16x32_bf16 v[30:33], v[90:93], v[212:215], 0
	v_mfma_f32_16x16x32_bf16 v[26:29], v[98:101], v[212:215], 0
	v_mfma_f32_16x16x32_bf16 v[6:9], v[90:93], v[220:223], 0
	v_mfma_f32_16x16x32_bf16 v[2:5], v[98:101], v[220:223], 0
	v_mfma_f32_16x16x32_bf16 v[62:65], v[94:97], v[166:169], v[62:65]
	v_mfma_f32_16x16x32_bf16 v[58:61], v[106:109], v[166:169], v[58:61]
	v_mfma_f32_16x16x32_bf16 v[46:49], v[94:97], v[208:211], v[46:49]
	v_mfma_f32_16x16x32_bf16 v[42:45], v[106:109], v[208:211], v[42:45]
	v_mfma_f32_16x16x32_bf16 v[30:33], v[94:97], v[216:219], v[30:33]
	v_mfma_f32_16x16x32_bf16 v[26:29], v[106:109], v[216:219], v[26:29]
	v_mfma_f32_16x16x32_bf16 v[6:9], v[94:97], v[224:227], v[6:9]
	v_mfma_f32_16x16x32_bf16 v[2:5], v[106:109], v[224:227], v[2:5]
	s_setprio 0
	s_barrier
	s_branch .Lpeel_mid_1737
